# v11 + B1/A1 k-loops: first two phases of each tile peeled, first-touch MFMAs take SrcC=0, accumulator zeroing removed
# speedup vs baseline: 1.0060x; 1.0044x over previous
.LBB0_155:
	s_ashr_i32 s23, s22, 31
	s_lshl_b64 s[8:9], s[22:23], 19
	s_add_u32 s24, s30, s8
	s_addc_u32 s25, s31, s9
	s_and_b64 s[8:9], s[4:5], exec
	s_cselect_b32 s3, s25, s1
	s_cselect_b32 s23, s24, s0
	s_ashr_i32 s21, s20, 31
	s_lshl_b64 s[8:9], s[20:21], 19
	s_add_u32 s26, s34, s8
	s_addc_u32 s27, s35, s9
	s_and_b64 s[8:9], s[4:5], exec
	s_cselect_b32 s21, s27, s7
	s_cselect_b32 s28, s26, s6
	s_add_u32 s0, s0, 0x40080
	s_addc_u32 s1, s1, 0
	s_add_u32 s29, s6, 0x100
	s_addc_u32 s42, s7, 0
	s_mov_b32 s49, -2
	s_add_u32 s6, s0, 0xfffc0080
	s_addc_u32 s7, s1, -1
	s_add_i32 s50, 16, 0x10000
	s_cmp_eq_u32 s49, 12
	s_cselect_b32 s9, s3, s7
	s_cselect_b32 s8, s23, s6
	v_add_u32_e32 v151, s50, v176
	s_cselect_b32 s7, s21, s42
	s_cselect_b32 s6, s28, s29
	s_add_i32 s52, 16, 0x14000
	ds_read_b128 v[132:135], v151
	ds_read_b128 v[152:155], v151 offset:1024
	ds_read_b128 v[156:159], v151 offset:2048
	ds_read_b128 v[160:163], v151 offset:3072
	v_add_u32_e32 v151, s52, v176
	ds_read_b128 v[164:167], v151
	ds_read_b128 v[168:171], v151 offset:1024
	ds_read_b128 v[172:175], v151 offset:2048
	ds_read_b128 v[180:183], v151 offset:3072
	v_lshl_add_u64 v[216:217], s[0:1], 0, v[146:147]
	s_add_i32 m0, s37, 0xc000
	ds_read_b128 v[184:187], v178
	ds_read_b128 v[188:191], v178 offset:1024
	ds_read_b128 v[192:195], v178 offset:2048
	ds_read_b128 v[196:199], v178 offset:3072
	ds_read_b128 v[200:203], v178 offset:4096
	ds_read_b128 v[204:207], v178 offset:5120
	ds_read_b128 v[208:211], v178 offset:6144
	ds_read_b128 v[212:215], v178 offset:7168
	global_load_lds_dwordx4 v[216:217], off
	v_lshl_add_u64 v[216:217], s[0:1], 0, v[148:149]
	s_add_i32 m0, s37, 0xe000
	s_nop 0
	global_load_lds_dwordx4 v[216:217], off
	s_waitcnt vmcnt(8)
	s_waitcnt lgkmcnt(0)
	s_barrier
	s_setprio 1
	s_waitcnt lgkmcnt(0)
	v_mfma_f32_16x16x32_bf16 v[128:131], v[132:135], v[184:187], 0
	v_mfma_f32_16x16x32_bf16 v[124:127], v[156:159], v[184:187], 0
	v_mfma_f32_16x16x32_bf16 v[112:115], v[132:135], v[192:195], 0
	v_mfma_f32_16x16x32_bf16 v[108:111], v[156:159], v[192:195], 0
	v_mfma_f32_16x16x32_bf16 v[96:99], v[132:135], v[200:203], 0
	v_mfma_f32_16x16x32_bf16 v[92:95], v[156:159], v[200:203], 0
	v_mfma_f32_16x16x32_bf16 v[80:83], v[132:135], v[208:211], 0
	v_mfma_f32_16x16x32_bf16 v[76:79], v[156:159], v[208:211], 0
	v_mfma_f32_16x16x32_bf16 v[128:131], v[152:155], v[188:191], v[128:131]
	v_mfma_f32_16x16x32_bf16 v[124:127], v[160:163], v[188:191], v[124:127]
	v_mfma_f32_16x16x32_bf16 v[112:115], v[152:155], v[196:199], v[112:115]
	v_mfma_f32_16x16x32_bf16 v[108:111], v[160:163], v[196:199], v[108:111]
	v_mfma_f32_16x16x32_bf16 v[96:99], v[152:155], v[204:207], v[96:99]
	v_mfma_f32_16x16x32_bf16 v[92:95], v[160:163], v[204:207], v[92:95]
	v_mfma_f32_16x16x32_bf16 v[80:83], v[152:155], v[212:215], v[80:83]
	v_mfma_f32_16x16x32_bf16 v[76:79], v[160:163], v[212:215], v[76:79]
	s_setprio 0
	s_setprio 1
	v_mfma_f32_16x16x32_bf16 v[120:123], v[164:167], v[184:187], 0
	v_mfma_f32_16x16x32_bf16 v[116:119], v[172:175], v[184:187], 0
	v_mfma_f32_16x16x32_bf16 v[104:107], v[164:167], v[192:195], 0
	v_mfma_f32_16x16x32_bf16 v[100:103], v[172:175], v[192:195], 0
	v_mfma_f32_16x16x32_bf16 v[88:91], v[164:167], v[200:203], 0
	v_mfma_f32_16x16x32_bf16 v[84:87], v[172:175], v[200:203], 0
	v_mfma_f32_16x16x32_bf16 v[72:75], v[164:167], v[208:211], 0
	v_mfma_f32_16x16x32_bf16 v[68:71], v[172:175], v[208:211], 0
	v_mfma_f32_16x16x32_bf16 v[120:123], v[168:171], v[188:191], v[120:123]
	v_mfma_f32_16x16x32_bf16 v[116:119], v[180:183], v[188:191], v[116:119]
	v_mfma_f32_16x16x32_bf16 v[104:107], v[168:171], v[196:199], v[104:107]
	v_mfma_f32_16x16x32_bf16 v[100:103], v[180:183], v[196:199], v[100:103]
	v_mfma_f32_16x16x32_bf16 v[88:91], v[168:171], v[204:207], v[88:91]
	v_mfma_f32_16x16x32_bf16 v[84:87], v[180:183], v[204:207], v[84:87]
	v_mfma_f32_16x16x32_bf16 v[72:75], v[168:171], v[212:215], v[72:75]
	v_mfma_f32_16x16x32_bf16 v[68:71], v[180:183], v[212:215], v[68:71]
	s_setprio 0
	s_barrier
	s_add_i32 s50, s50, s36
	v_lshl_add_u64 v[216:217], s[6:7], 0, v[138:139]
	s_mov_b32 m0, s50
	ds_read_b128 v[184:187], v178 offset:16384
	ds_read_b128 v[188:191], v178 offset:17408
	ds_read_b128 v[192:195], v178 offset:18432
	ds_read_b128 v[196:199], v178 offset:19456
	ds_read_b128 v[200:203], v178 offset:20480
	ds_read_b128 v[204:207], v178 offset:21504
	ds_read_b128 v[208:211], v178 offset:22528
	ds_read_b128 v[212:215], v178 offset:23552
	global_load_lds_dwordx4 v[216:217], off
	s_add_i32 m0, s50, 0x2000
	s_add_u32 s50, s6, 0x40000
	v_lshl_add_u64 v[218:219], s[6:7], 0, v[0:1]
	s_addc_u32 s51, s7, 0
	s_add_i32 s52, s52, s36
	global_load_lds_dwordx4 v[218:219], off
	v_lshl_add_u64 v[220:221], s[50:51], 0, v[138:139]
	s_mov_b32 m0, s52
	v_lshl_add_u64 v[224:225], s[8:9], 0, v[136:137]
	global_load_lds_dwordx4 v[220:221], off
	v_lshl_add_u64 v[220:221], s[50:51], 0, v[0:1]
	s_add_i32 m0, s52, 0x2000
	s_nop 0
	global_load_lds_dwordx4 v[220:221], off
	v_lshl_add_u64 v[220:221], s[8:9], 0, v[140:141]
	s_waitcnt vmcnt(6)
	s_waitcnt lgkmcnt(0)
	s_barrier
	s_setprio 1
	s_waitcnt lgkmcnt(0)
	v_mfma_f32_16x16x32_bf16 v[64:67], v[132:135], v[184:187], 0
	v_mfma_f32_16x16x32_bf16 v[60:63], v[156:159], v[184:187], 0
	v_mfma_f32_16x16x32_bf16 v[48:51], v[132:135], v[192:195], 0
	v_mfma_f32_16x16x32_bf16 v[44:47], v[156:159], v[192:195], 0
	v_mfma_f32_16x16x32_bf16 v[32:35], v[132:135], v[200:203], 0
	v_mfma_f32_16x16x32_bf16 v[28:31], v[156:159], v[200:203], 0
	v_mfma_f32_16x16x32_bf16 v[16:19], v[132:135], v[208:211], 0
	v_mfma_f32_16x16x32_bf16 v[12:15], v[156:159], v[208:211], 0
	v_mfma_f32_16x16x32_bf16 v[64:67], v[152:155], v[188:191], v[64:67]
	v_mfma_f32_16x16x32_bf16 v[60:63], v[160:163], v[188:191], v[60:63]
	v_mfma_f32_16x16x32_bf16 v[48:51], v[152:155], v[196:199], v[48:51]
	v_mfma_f32_16x16x32_bf16 v[44:47], v[160:163], v[196:199], v[44:47]
	v_mfma_f32_16x16x32_bf16 v[32:35], v[152:155], v[204:207], v[32:35]
	v_mfma_f32_16x16x32_bf16 v[28:31], v[160:163], v[204:207], v[28:31]
	v_mfma_f32_16x16x32_bf16 v[16:19], v[152:155], v[212:215], v[16:19]
	v_mfma_f32_16x16x32_bf16 v[12:15], v[160:163], v[212:215], v[12:15]
	s_setprio 0
	s_setprio 1
	v_mfma_f32_16x16x32_bf16 v[56:59], v[164:167], v[184:187], 0
	v_mfma_f32_16x16x32_bf16 v[52:55], v[172:175], v[184:187], 0
	v_mfma_f32_16x16x32_bf16 v[40:43], v[164:167], v[192:195], 0
	v_mfma_f32_16x16x32_bf16 v[36:39], v[172:175], v[192:195], 0
	v_mfma_f32_16x16x32_bf16 v[24:27], v[164:167], v[200:203], 0
	v_mfma_f32_16x16x32_bf16 v[20:23], v[172:175], v[200:203], 0
	v_mfma_f32_16x16x32_bf16 v[8:11], v[164:167], v[208:211], 0
	v_mfma_f32_16x16x32_bf16 v[4:7], v[172:175], v[208:211], 0
	v_mfma_f32_16x16x32_bf16 v[56:59], v[168:171], v[188:191], v[56:59]
	v_mfma_f32_16x16x32_bf16 v[52:55], v[180:183], v[188:191], v[52:55]
	v_mfma_f32_16x16x32_bf16 v[40:43], v[168:171], v[196:199], v[40:43]
	v_mfma_f32_16x16x32_bf16 v[36:39], v[180:183], v[196:199], v[36:39]
	v_mfma_f32_16x16x32_bf16 v[24:27], v[168:171], v[204:207], v[24:27]
	v_mfma_f32_16x16x32_bf16 v[20:23], v[180:183], v[204:207], v[20:23]
	v_mfma_f32_16x16x32_bf16 v[8:11], v[168:171], v[212:215], v[8:11]
	v_mfma_f32_16x16x32_bf16 v[4:7], v[180:183], v[212:215], v[4:7]
	s_setprio 0
	s_barrier
	s_branch .Lb1_ph3

.Lb1_ph3:
	s_add_i32 s50, 16, 0x18000
	v_add_u32_e32 v151, s50, v176
	s_add_i32 s51, 16, 0x1c000
	ds_read_b128 v[132:135], v151
	ds_read_b128 v[152:155], v151 offset:1024
	ds_read_b128 v[156:159], v151 offset:2048
	ds_read_b128 v[160:163], v151 offset:3072
	v_add_u32_e32 v151, s51, v176
	ds_read_b128 v[164:167], v151
	ds_read_b128 v[168:171], v151 offset:1024
	ds_read_b128 v[172:175], v151 offset:2048
	ds_read_b128 v[180:183], v151 offset:3072
	s_mov_b32 m0, s37
	s_nop 0
	global_load_lds_dwordx4 v[220:221], off
	s_mov_b32 m0, s38
	s_nop 0
	global_load_lds_dwordx4 v[224:225], off
	s_add_u32 s8, s8, 0x40000
	s_addc_u32 s9, s9, 0
	s_mov_b32 m0, s39
	v_lshl_add_u64 v[226:227], s[8:9], 0, v[140:141]
	ds_read_b128 v[184:187], v178 offset:32768
	ds_read_b128 v[188:191], v178 offset:33792
	ds_read_b128 v[192:195], v178 offset:34816
	ds_read_b128 v[196:199], v178 offset:35840
	ds_read_b128 v[200:203], v178 offset:36864
	ds_read_b128 v[204:207], v178 offset:37888
	ds_read_b128 v[208:211], v178 offset:38912
	ds_read_b128 v[212:215], v178 offset:39936
	global_load_lds_dwordx4 v[226:227], off
	v_lshl_add_u64 v[226:227], s[8:9], 0, v[136:137]
	s_mov_b32 m0, s40
	s_nop 0
	global_load_lds_dwordx4 v[226:227], off
	s_waitcnt vmcnt(8)
	s_waitcnt lgkmcnt(0)
	s_barrier
	s_setprio 1
	s_waitcnt lgkmcnt(0)
	v_mfma_f32_16x16x32_bf16 v[128:131], v[132:135], v[184:187], v[128:131]
	v_mfma_f32_16x16x32_bf16 v[124:127], v[156:159], v[184:187], v[124:127]
	v_mfma_f32_16x16x32_bf16 v[112:115], v[132:135], v[192:195], v[112:115]
	v_mfma_f32_16x16x32_bf16 v[108:111], v[156:159], v[192:195], v[108:111]
	v_mfma_f32_16x16x32_bf16 v[96:99], v[132:135], v[200:203], v[96:99]
	v_mfma_f32_16x16x32_bf16 v[92:95], v[156:159], v[200:203], v[92:95]
	v_mfma_f32_16x16x32_bf16 v[80:83], v[132:135], v[208:211], v[80:83]
	v_mfma_f32_16x16x32_bf16 v[76:79], v[156:159], v[208:211], v[76:79]
	v_mfma_f32_16x16x32_bf16 v[128:131], v[152:155], v[188:191], v[128:131]
	v_mfma_f32_16x16x32_bf16 v[124:127], v[160:163], v[188:191], v[124:127]
	v_mfma_f32_16x16x32_bf16 v[112:115], v[152:155], v[196:199], v[112:115]
	v_mfma_f32_16x16x32_bf16 v[108:111], v[160:163], v[196:199], v[108:111]
	v_mfma_f32_16x16x32_bf16 v[96:99], v[152:155], v[204:207], v[96:99]
	v_mfma_f32_16x16x32_bf16 v[92:95], v[160:163], v[204:207], v[92:95]
	v_mfma_f32_16x16x32_bf16 v[80:83], v[152:155], v[212:215], v[80:83]
	v_mfma_f32_16x16x32_bf16 v[76:79], v[160:163], v[212:215], v[76:79]
	s_setprio 0
	s_setprio 1
	v_mfma_f32_16x16x32_bf16 v[120:123], v[164:167], v[184:187], v[120:123]
	v_mfma_f32_16x16x32_bf16 v[116:119], v[172:175], v[184:187], v[116:119]
	v_mfma_f32_16x16x32_bf16 v[104:107], v[164:167], v[192:195], v[104:107]
	v_mfma_f32_16x16x32_bf16 v[100:103], v[172:175], v[192:195], v[100:103]
	v_mfma_f32_16x16x32_bf16 v[88:91], v[164:167], v[200:203], v[88:91]
	v_mfma_f32_16x16x32_bf16 v[84:87], v[172:175], v[200:203], v[84:87]
	v_mfma_f32_16x16x32_bf16 v[72:75], v[164:167], v[208:211], v[72:75]
	v_mfma_f32_16x16x32_bf16 v[68:71], v[172:175], v[208:211], v[68:71]
	v_mfma_f32_16x16x32_bf16 v[120:123], v[168:171], v[188:191], v[120:123]
	v_mfma_f32_16x16x32_bf16 v[116:119], v[180:183], v[188:191], v[116:119]
	v_mfma_f32_16x16x32_bf16 v[104:107], v[168:171], v[196:199], v[104:107]
	v_mfma_f32_16x16x32_bf16 v[100:103], v[180:183], v[196:199], v[100:103]
	v_mfma_f32_16x16x32_bf16 v[88:91], v[168:171], v[204:207], v[88:91]
	v_mfma_f32_16x16x32_bf16 v[84:87], v[180:183], v[204:207], v[84:87]
	v_mfma_f32_16x16x32_bf16 v[72:75], v[168:171], v[212:215], v[72:75]
	v_mfma_f32_16x16x32_bf16 v[68:71], v[180:183], v[212:215], v[68:71]
	s_setprio 0
	s_barrier
	s_add_i32 s8, s50, s36
	v_lshl_add_u64 v[216:217], v[216:217], 0, s[84:85]
	s_mov_b32 m0, s8
	ds_read_b128 v[184:187], v178 offset:49152
	ds_read_b128 v[188:191], v178 offset:50176
	ds_read_b128 v[192:195], v178 offset:51200
	ds_read_b128 v[196:199], v178 offset:52224
	ds_read_b128 v[200:203], v178 offset:53248
	ds_read_b128 v[204:207], v178 offset:54272
	ds_read_b128 v[208:211], v178 offset:55296
	ds_read_b128 v[212:215], v178 offset:56320
	global_load_lds_dwordx4 v[216:217], off
	s_add_i32 m0, s8, 0x2000
	s_add_u32 s6, s6, 0x40080
	v_lshl_add_u64 v[216:217], v[218:219], 0, s[84:85]
	s_addc_u32 s7, s7, 0
	s_add_i32 s8, s51, s36
	global_load_lds_dwordx4 v[216:217], off
	v_lshl_add_u64 v[216:217], s[6:7], 0, v[138:139]
	s_mov_b32 m0, s8
	s_nop 0
	global_load_lds_dwordx4 v[216:217], off
	v_lshl_add_u64 v[216:217], s[6:7], 0, v[0:1]
	s_add_i32 m0, s8, 0x2000
	s_nop 0
	global_load_lds_dwordx4 v[216:217], off
	v_lshl_add_u64 v[216:217], v[220:221], 0, s[84:85]
	s_mov_b32 m0, s44
	s_nop 0
	global_load_lds_dwordx4 v[216:217], off
	v_lshl_add_u64 v[216:217], v[224:225], 0, s[84:85]
	s_mov_b32 m0, s45
	s_nop 0
	global_load_lds_dwordx4 v[216:217], off
	s_waitcnt vmcnt(8)
	s_waitcnt lgkmcnt(0)
	s_barrier
	s_setprio 1
	s_waitcnt lgkmcnt(0)
	v_mfma_f32_16x16x32_bf16 v[64:67], v[132:135], v[184:187], v[64:67]
	v_mfma_f32_16x16x32_bf16 v[60:63], v[156:159], v[184:187], v[60:63]
	v_mfma_f32_16x16x32_bf16 v[48:51], v[132:135], v[192:195], v[48:51]
	v_mfma_f32_16x16x32_bf16 v[44:47], v[156:159], v[192:195], v[44:47]
	v_mfma_f32_16x16x32_bf16 v[32:35], v[132:135], v[200:203], v[32:35]
	v_mfma_f32_16x16x32_bf16 v[28:31], v[156:159], v[200:203], v[28:31]
	v_mfma_f32_16x16x32_bf16 v[16:19], v[132:135], v[208:211], v[16:19]
	v_mfma_f32_16x16x32_bf16 v[12:15], v[156:159], v[208:211], v[12:15]
	v_mfma_f32_16x16x32_bf16 v[64:67], v[152:155], v[188:191], v[64:67]
	v_mfma_f32_16x16x32_bf16 v[60:63], v[160:163], v[188:191], v[60:63]
	v_mfma_f32_16x16x32_bf16 v[48:51], v[152:155], v[196:199], v[48:51]
	v_mfma_f32_16x16x32_bf16 v[44:47], v[160:163], v[196:199], v[44:47]
	v_mfma_f32_16x16x32_bf16 v[32:35], v[152:155], v[204:207], v[32:35]
	v_mfma_f32_16x16x32_bf16 v[28:31], v[160:163], v[204:207], v[28:31]
	v_mfma_f32_16x16x32_bf16 v[16:19], v[152:155], v[212:215], v[16:19]
	v_mfma_f32_16x16x32_bf16 v[12:15], v[160:163], v[212:215], v[12:15]
	s_setprio 0
	s_setprio 1
	v_mfma_f32_16x16x32_bf16 v[56:59], v[164:167], v[184:187], v[56:59]
	v_mfma_f32_16x16x32_bf16 v[52:55], v[172:175], v[184:187], v[52:55]
	v_mfma_f32_16x16x32_bf16 v[40:43], v[164:167], v[192:195], v[40:43]
	v_mfma_f32_16x16x32_bf16 v[36:39], v[172:175], v[192:195], v[36:39]
	v_mfma_f32_16x16x32_bf16 v[24:27], v[164:167], v[200:203], v[24:27]
	v_mfma_f32_16x16x32_bf16 v[20:23], v[172:175], v[200:203], v[20:23]
	v_mfma_f32_16x16x32_bf16 v[8:11], v[164:167], v[208:211], v[8:11]
	v_mfma_f32_16x16x32_bf16 v[4:7], v[172:175], v[208:211], v[4:7]
	v_mfma_f32_16x16x32_bf16 v[56:59], v[168:171], v[188:191], v[56:59]
	v_mfma_f32_16x16x32_bf16 v[52:55], v[180:183], v[188:191], v[52:55]
	v_mfma_f32_16x16x32_bf16 v[40:43], v[168:171], v[196:199], v[40:43]
	v_mfma_f32_16x16x32_bf16 v[36:39], v[180:183], v[196:199], v[36:39]
	v_mfma_f32_16x16x32_bf16 v[24:27], v[168:171], v[204:207], v[24:27]
	v_mfma_f32_16x16x32_bf16 v[20:23], v[180:183], v[204:207], v[20:23]
	v_mfma_f32_16x16x32_bf16 v[8:11], v[168:171], v[212:215], v[8:11]
	v_mfma_f32_16x16x32_bf16 v[4:7], v[180:183], v[212:215], v[4:7]
	s_setprio 0
	s_barrier
	s_add_i32 s49, s49, 2
	s_add_u32 s0, s0, 0x100
	s_addc_u32 s1, s1, 0
	s_add_u32 s29, s29, 0x100
	s_addc_u32 s42, s42, 0
	s_cmp_gt_u32 s49, 13
	s_cbranch_scc0 .LBB0_156
	s_and_b64 vcc, exec, s[18:19]
	s_cbranch_vccz .LBB0_159
	s_barrier

.LBB0_445:
	s_ashr_i32 s23, s22, 31
	s_lshl_b64 s[24:25], s[22:23], 19
	s_add_u32 s24, s34, s24
	s_addc_u32 s25, s35, s25
	s_and_b64 s[26:27], s[6:7], exec
	s_cselect_b32 s3, s25, s1
	s_cselect_b32 s23, s24, s0
	s_ashr_i32 s21, s20, 31
	s_lshl_b64 s[26:27], s[20:21], 19
	s_add_u32 s26, s36, s26
	s_addc_u32 s27, s37, s27
	s_and_b64 s[30:31], s[6:7], exec
	s_cselect_b32 s21, s27, s29
	s_cselect_b32 s48, s26, s28
	s_add_u32 s0, s0, 0x40080
	s_addc_u32 s1, s1, 0
	s_add_u32 s49, s28, 0x100
	s_addc_u32 s50, s29, 0
	s_mov_b32 s51, -2
	s_waitcnt vmcnt(0)
	s_add_u32 s28, s0, 0xfffc0080
	s_addc_u32 s29, s1, -1
	s_add_i32 s52, 16, 0x10000
	s_cmp_eq_u32 s51, 12
	s_cselect_b32 s31, s3, s29
	s_cselect_b32 s30, s23, s28
	v_add_u32_e32 v3, s52, v175
	s_cselect_b32 s29, s21, s50
	s_cselect_b32 s28, s48, s49
	s_add_i32 s54, 16, 0x14000
	ds_read_b128 v[142:145], v3
	s_waitcnt lgkmcnt(0)
	ds_read_b128 v[146:149], v3 offset:1024
	ds_read_b128 v[150:153], v3 offset:2048
	ds_read_b128 v[154:157], v3 offset:3072
	v_add_u32_e32 v3, s54, v175
	ds_read_b128 v[158:161], v3
	ds_read_b128 v[162:165], v3 offset:1024
	ds_read_b128 v[166:169], v3 offset:2048
	ds_read_b128 v[170:173], v3 offset:3072
	v_lshl_add_u64 v[210:211], s[0:1], 0, v[138:139]
	s_add_i32 m0, s39, 0xc000
	ds_read_b128 v[178:181], v177
	ds_read_b128 v[182:185], v177 offset:1024
	ds_read_b128 v[186:189], v177 offset:2048
	ds_read_b128 v[190:193], v177 offset:3072
	ds_read_b128 v[194:197], v177 offset:4096
	ds_read_b128 v[198:201], v177 offset:5120
	ds_read_b128 v[202:205], v177 offset:6144
	ds_read_b128 v[206:209], v177 offset:7168
	global_load_lds_dwordx4 v[210:211], off
	v_lshl_add_u64 v[210:211], s[0:1], 0, v[140:141]
	s_add_i32 m0, s39, 0xe000
	s_nop 0
	global_load_lds_dwordx4 v[210:211], off
	s_waitcnt vmcnt(8)
	s_waitcnt lgkmcnt(0)
	s_barrier
	s_setprio 1
	s_waitcnt lgkmcnt(0)
	v_mfma_f32_16x16x32_bf16 v[128:131], v[142:145], v[178:181], 0
	v_mfma_f32_16x16x32_bf16 v[120:123], v[150:153], v[178:181], 0
	v_mfma_f32_16x16x32_bf16 v[112:115], v[142:145], v[186:189], 0
	v_mfma_f32_16x16x32_bf16 v[104:107], v[150:153], v[186:189], 0
	v_mfma_f32_16x16x32_bf16 v[96:99], v[142:145], v[194:197], 0
	v_mfma_f32_16x16x32_bf16 v[88:91], v[150:153], v[194:197], 0
	v_mfma_f32_16x16x32_bf16 v[80:83], v[142:145], v[202:205], 0
	v_mfma_f32_16x16x32_bf16 v[72:75], v[150:153], v[202:205], 0
	v_mfma_f32_16x16x32_bf16 v[128:131], v[146:149], v[182:185], v[128:131]
	v_mfma_f32_16x16x32_bf16 v[120:123], v[154:157], v[182:185], v[120:123]
	v_mfma_f32_16x16x32_bf16 v[112:115], v[146:149], v[190:193], v[112:115]
	v_mfma_f32_16x16x32_bf16 v[104:107], v[154:157], v[190:193], v[104:107]
	v_mfma_f32_16x16x32_bf16 v[96:99], v[146:149], v[198:201], v[96:99]
	v_mfma_f32_16x16x32_bf16 v[88:91], v[154:157], v[198:201], v[88:91]
	v_mfma_f32_16x16x32_bf16 v[80:83], v[146:149], v[206:209], v[80:83]
	v_mfma_f32_16x16x32_bf16 v[72:75], v[154:157], v[206:209], v[72:75]
	s_setprio 0
	s_setprio 1
	v_mfma_f32_16x16x32_bf16 v[124:127], v[158:161], v[178:181], 0
	v_mfma_f32_16x16x32_bf16 v[116:119], v[166:169], v[178:181], 0
	v_mfma_f32_16x16x32_bf16 v[108:111], v[158:161], v[186:189], 0
	v_mfma_f32_16x16x32_bf16 v[100:103], v[166:169], v[186:189], 0
	v_mfma_f32_16x16x32_bf16 v[92:95], v[158:161], v[194:197], 0
	v_mfma_f32_16x16x32_bf16 v[84:87], v[166:169], v[194:197], 0
	v_mfma_f32_16x16x32_bf16 v[76:79], v[158:161], v[202:205], 0
	v_mfma_f32_16x16x32_bf16 v[68:71], v[166:169], v[202:205], 0
	v_mfma_f32_16x16x32_bf16 v[124:127], v[162:165], v[182:185], v[124:127]
	v_mfma_f32_16x16x32_bf16 v[116:119], v[170:173], v[182:185], v[116:119]
	v_mfma_f32_16x16x32_bf16 v[108:111], v[162:165], v[190:193], v[108:111]
	v_mfma_f32_16x16x32_bf16 v[100:103], v[170:173], v[190:193], v[100:103]
	v_mfma_f32_16x16x32_bf16 v[92:95], v[162:165], v[198:201], v[92:95]
	v_mfma_f32_16x16x32_bf16 v[84:87], v[170:173], v[198:201], v[84:87]
	v_mfma_f32_16x16x32_bf16 v[76:79], v[162:165], v[206:209], v[76:79]
	v_mfma_f32_16x16x32_bf16 v[68:71], v[170:173], v[206:209], v[68:71]
	s_setprio 0
	s_barrier
	s_add_i32 s52, s52, s38
	v_lshl_add_u64 v[210:211], s[28:29], 0, v[134:135]
	s_mov_b32 m0, s52
	ds_read_b128 v[178:181], v177 offset:16384
	ds_read_b128 v[182:185], v177 offset:17408
	ds_read_b128 v[186:189], v177 offset:18432
	ds_read_b128 v[190:193], v177 offset:19456
	ds_read_b128 v[194:197], v177 offset:20480
	ds_read_b128 v[198:201], v177 offset:21504
	ds_read_b128 v[202:205], v177 offset:22528
	ds_read_b128 v[206:209], v177 offset:23552
	global_load_lds_dwordx4 v[210:211], off
	s_add_i32 m0, s52, 0x2000
	s_add_u32 s52, s28, 0x40000
	v_lshl_add_u64 v[212:213], s[28:29], 0, v[0:1]
	s_addc_u32 s53, s29, 0
	s_add_i32 s54, s54, s38
	global_load_lds_dwordx4 v[212:213], off
	v_lshl_add_u64 v[214:215], s[52:53], 0, v[134:135]
	s_mov_b32 m0, s54
	v_lshl_add_u64 v[216:217], s[30:31], 0, v[132:133]
	global_load_lds_dwordx4 v[214:215], off
	v_lshl_add_u64 v[214:215], s[52:53], 0, v[0:1]
	s_add_i32 m0, s54, 0x2000
	s_nop 0
	global_load_lds_dwordx4 v[214:215], off
	v_lshl_add_u64 v[214:215], s[30:31], 0, v[136:137]
	s_waitcnt vmcnt(6)
	s_waitcnt lgkmcnt(0)
	s_barrier
	s_setprio 1
	s_waitcnt lgkmcnt(0)
	v_mfma_f32_16x16x32_bf16 v[64:67], v[142:145], v[178:181], 0
	v_mfma_f32_16x16x32_bf16 v[56:59], v[150:153], v[178:181], 0
	v_mfma_f32_16x16x32_bf16 v[48:51], v[142:145], v[186:189], 0
	v_mfma_f32_16x16x32_bf16 v[40:43], v[150:153], v[186:189], 0
	v_mfma_f32_16x16x32_bf16 v[32:35], v[142:145], v[194:197], 0
	v_mfma_f32_16x16x32_bf16 v[24:27], v[150:153], v[194:197], 0
	v_mfma_f32_16x16x32_bf16 v[16:19], v[142:145], v[202:205], 0
	v_mfma_f32_16x16x32_bf16 v[8:11], v[150:153], v[202:205], 0
	v_mfma_f32_16x16x32_bf16 v[64:67], v[146:149], v[182:185], v[64:67]
	v_mfma_f32_16x16x32_bf16 v[56:59], v[154:157], v[182:185], v[56:59]
	v_mfma_f32_16x16x32_bf16 v[48:51], v[146:149], v[190:193], v[48:51]
	v_mfma_f32_16x16x32_bf16 v[40:43], v[154:157], v[190:193], v[40:43]
	v_mfma_f32_16x16x32_bf16 v[32:35], v[146:149], v[198:201], v[32:35]
	v_mfma_f32_16x16x32_bf16 v[24:27], v[154:157], v[198:201], v[24:27]
	v_mfma_f32_16x16x32_bf16 v[16:19], v[146:149], v[206:209], v[16:19]
	v_mfma_f32_16x16x32_bf16 v[8:11], v[154:157], v[206:209], v[8:11]
	s_setprio 0
	s_setprio 1
	v_mfma_f32_16x16x32_bf16 v[60:63], v[158:161], v[178:181], 0
	v_mfma_f32_16x16x32_bf16 v[52:55], v[166:169], v[178:181], 0
	v_mfma_f32_16x16x32_bf16 v[44:47], v[158:161], v[186:189], 0
	v_mfma_f32_16x16x32_bf16 v[36:39], v[166:169], v[186:189], 0
	v_mfma_f32_16x16x32_bf16 v[28:31], v[158:161], v[194:197], 0
	v_mfma_f32_16x16x32_bf16 v[20:23], v[166:169], v[194:197], 0
	v_mfma_f32_16x16x32_bf16 v[12:15], v[158:161], v[202:205], 0
	v_mfma_f32_16x16x32_bf16 v[4:7], v[166:169], v[202:205], 0
	v_mfma_f32_16x16x32_bf16 v[60:63], v[162:165], v[182:185], v[60:63]
	v_mfma_f32_16x16x32_bf16 v[52:55], v[170:173], v[182:185], v[52:55]
	v_mfma_f32_16x16x32_bf16 v[44:47], v[162:165], v[190:193], v[44:47]
	v_mfma_f32_16x16x32_bf16 v[36:39], v[170:173], v[190:193], v[36:39]
	v_mfma_f32_16x16x32_bf16 v[28:31], v[162:165], v[198:201], v[28:31]
	v_mfma_f32_16x16x32_bf16 v[20:23], v[170:173], v[198:201], v[20:23]
	v_mfma_f32_16x16x32_bf16 v[12:15], v[162:165], v[206:209], v[12:15]
	v_mfma_f32_16x16x32_bf16 v[4:7], v[170:173], v[206:209], v[4:7]
	s_setprio 0
	s_barrier
	s_branch .La1_ph3

.La1_ph3:
	s_add_i32 s52, 16, 0x18000
	v_add_u32_e32 v3, s52, v175
	s_add_i32 s53, 16, 0x1c000
	ds_read_b128 v[142:145], v3
	ds_read_b128 v[146:149], v3 offset:1024
	ds_read_b128 v[150:153], v3 offset:2048
	ds_read_b128 v[154:157], v3 offset:3072
	v_add_u32_e32 v3, s53, v175
	ds_read_b128 v[158:161], v3
	ds_read_b128 v[162:165], v3 offset:1024
	ds_read_b128 v[166:169], v3 offset:2048
	ds_read_b128 v[170:173], v3 offset:3072
	s_mov_b32 m0, s39
	s_nop 0
	global_load_lds_dwordx4 v[214:215], off
	s_mov_b32 m0, s40
	s_nop 0
	global_load_lds_dwordx4 v[216:217], off
	s_add_u32 s30, s30, 0x40000
	s_addc_u32 s31, s31, 0
	s_mov_b32 m0, s41
	v_lshl_add_u64 v[218:219], s[30:31], 0, v[136:137]
	ds_read_b128 v[178:181], v177 offset:32768
	ds_read_b128 v[182:185], v177 offset:33792
	ds_read_b128 v[186:189], v177 offset:34816
	ds_read_b128 v[190:193], v177 offset:35840
	ds_read_b128 v[194:197], v177 offset:36864
	ds_read_b128 v[198:201], v177 offset:37888
	ds_read_b128 v[202:205], v177 offset:38912
	ds_read_b128 v[206:209], v177 offset:39936
	global_load_lds_dwordx4 v[218:219], off
	v_lshl_add_u64 v[218:219], s[30:31], 0, v[132:133]
	s_mov_b32 m0, s42
	s_nop 0
	global_load_lds_dwordx4 v[218:219], off
	s_waitcnt vmcnt(8)
	s_waitcnt lgkmcnt(0)
	s_barrier
	s_setprio 1
	s_waitcnt lgkmcnt(0)
	v_mfma_f32_16x16x32_bf16 v[128:131], v[142:145], v[178:181], v[128:131]
	v_mfma_f32_16x16x32_bf16 v[120:123], v[150:153], v[178:181], v[120:123]
	v_mfma_f32_16x16x32_bf16 v[112:115], v[142:145], v[186:189], v[112:115]
	v_mfma_f32_16x16x32_bf16 v[104:107], v[150:153], v[186:189], v[104:107]
	v_mfma_f32_16x16x32_bf16 v[96:99], v[142:145], v[194:197], v[96:99]
	v_mfma_f32_16x16x32_bf16 v[88:91], v[150:153], v[194:197], v[88:91]
	v_mfma_f32_16x16x32_bf16 v[80:83], v[142:145], v[202:205], v[80:83]
	v_mfma_f32_16x16x32_bf16 v[72:75], v[150:153], v[202:205], v[72:75]
	v_mfma_f32_16x16x32_bf16 v[128:131], v[146:149], v[182:185], v[128:131]
	v_mfma_f32_16x16x32_bf16 v[120:123], v[154:157], v[182:185], v[120:123]
	v_mfma_f32_16x16x32_bf16 v[112:115], v[146:149], v[190:193], v[112:115]
	v_mfma_f32_16x16x32_bf16 v[104:107], v[154:157], v[190:193], v[104:107]
	v_mfma_f32_16x16x32_bf16 v[96:99], v[146:149], v[198:201], v[96:99]
	v_mfma_f32_16x16x32_bf16 v[88:91], v[154:157], v[198:201], v[88:91]
	v_mfma_f32_16x16x32_bf16 v[80:83], v[146:149], v[206:209], v[80:83]
	v_mfma_f32_16x16x32_bf16 v[72:75], v[154:157], v[206:209], v[72:75]
	s_setprio 0
	s_setprio 1
	v_mfma_f32_16x16x32_bf16 v[124:127], v[158:161], v[178:181], v[124:127]
	v_mfma_f32_16x16x32_bf16 v[116:119], v[166:169], v[178:181], v[116:119]
	v_mfma_f32_16x16x32_bf16 v[108:111], v[158:161], v[186:189], v[108:111]
	v_mfma_f32_16x16x32_bf16 v[100:103], v[166:169], v[186:189], v[100:103]
	v_mfma_f32_16x16x32_bf16 v[92:95], v[158:161], v[194:197], v[92:95]
	v_mfma_f32_16x16x32_bf16 v[84:87], v[166:169], v[194:197], v[84:87]
	v_mfma_f32_16x16x32_bf16 v[76:79], v[158:161], v[202:205], v[76:79]
	v_mfma_f32_16x16x32_bf16 v[68:71], v[166:169], v[202:205], v[68:71]
	v_mfma_f32_16x16x32_bf16 v[124:127], v[162:165], v[182:185], v[124:127]
	v_mfma_f32_16x16x32_bf16 v[116:119], v[170:173], v[182:185], v[116:119]
	v_mfma_f32_16x16x32_bf16 v[108:111], v[162:165], v[190:193], v[108:111]
	v_mfma_f32_16x16x32_bf16 v[100:103], v[170:173], v[190:193], v[100:103]
	v_mfma_f32_16x16x32_bf16 v[92:95], v[162:165], v[198:201], v[92:95]
	v_mfma_f32_16x16x32_bf16 v[84:87], v[170:173], v[198:201], v[84:87]
	v_mfma_f32_16x16x32_bf16 v[76:79], v[162:165], v[206:209], v[76:79]
	v_mfma_f32_16x16x32_bf16 v[68:71], v[170:173], v[206:209], v[68:71]
	s_setprio 0
	s_barrier
	s_add_i32 s30, s52, s38
	v_lshl_add_u64 v[210:211], v[210:211], 0, s[84:85]
	s_mov_b32 m0, s30
	ds_read_b128 v[178:181], v177 offset:49152
	ds_read_b128 v[182:185], v177 offset:50176
	ds_read_b128 v[186:189], v177 offset:51200
	ds_read_b128 v[190:193], v177 offset:52224
	ds_read_b128 v[194:197], v177 offset:53248
	ds_read_b128 v[198:201], v177 offset:54272
	ds_read_b128 v[202:205], v177 offset:55296
	ds_read_b128 v[206:209], v177 offset:56320
	global_load_lds_dwordx4 v[210:211], off
	s_add_i32 m0, s30, 0x2000
	s_add_u32 s28, s28, 0x40080
	v_lshl_add_u64 v[210:211], v[212:213], 0, s[84:85]
	s_addc_u32 s29, s29, 0
	s_add_i32 s30, s53, s38
	global_load_lds_dwordx4 v[210:211], off
	v_lshl_add_u64 v[210:211], s[28:29], 0, v[134:135]
	s_mov_b32 m0, s30
	s_nop 0
	global_load_lds_dwordx4 v[210:211], off
	v_lshl_add_u64 v[210:211], s[28:29], 0, v[0:1]
	s_add_i32 m0, s30, 0x2000
	s_nop 0
	global_load_lds_dwordx4 v[210:211], off
	v_lshl_add_u64 v[210:211], v[214:215], 0, s[84:85]
	s_mov_b32 m0, s44
	s_nop 0
	global_load_lds_dwordx4 v[210:211], off
	v_lshl_add_u64 v[210:211], v[216:217], 0, s[84:85]
	s_mov_b32 m0, s45
	s_nop 0
	global_load_lds_dwordx4 v[210:211], off
	s_waitcnt vmcnt(8)
	s_waitcnt lgkmcnt(0)
	s_barrier
	s_setprio 1
	s_waitcnt lgkmcnt(0)
	v_mfma_f32_16x16x32_bf16 v[64:67], v[142:145], v[178:181], v[64:67]
	v_mfma_f32_16x16x32_bf16 v[56:59], v[150:153], v[178:181], v[56:59]
	v_mfma_f32_16x16x32_bf16 v[48:51], v[142:145], v[186:189], v[48:51]
	v_mfma_f32_16x16x32_bf16 v[40:43], v[150:153], v[186:189], v[40:43]
	v_mfma_f32_16x16x32_bf16 v[32:35], v[142:145], v[194:197], v[32:35]
	v_mfma_f32_16x16x32_bf16 v[24:27], v[150:153], v[194:197], v[24:27]
	v_mfma_f32_16x16x32_bf16 v[16:19], v[142:145], v[202:205], v[16:19]
	v_mfma_f32_16x16x32_bf16 v[8:11], v[150:153], v[202:205], v[8:11]
	v_mfma_f32_16x16x32_bf16 v[64:67], v[146:149], v[182:185], v[64:67]
	v_mfma_f32_16x16x32_bf16 v[56:59], v[154:157], v[182:185], v[56:59]
	v_mfma_f32_16x16x32_bf16 v[48:51], v[146:149], v[190:193], v[48:51]
	v_mfma_f32_16x16x32_bf16 v[40:43], v[154:157], v[190:193], v[40:43]
	v_mfma_f32_16x16x32_bf16 v[32:35], v[146:149], v[198:201], v[32:35]
	v_mfma_f32_16x16x32_bf16 v[24:27], v[154:157], v[198:201], v[24:27]
	v_mfma_f32_16x16x32_bf16 v[16:19], v[146:149], v[206:209], v[16:19]
	v_mfma_f32_16x16x32_bf16 v[8:11], v[154:157], v[206:209], v[8:11]
	s_setprio 0
	s_setprio 1
	v_mfma_f32_16x16x32_bf16 v[60:63], v[158:161], v[178:181], v[60:63]
	v_mfma_f32_16x16x32_bf16 v[52:55], v[166:169], v[178:181], v[52:55]
	v_mfma_f32_16x16x32_bf16 v[44:47], v[158:161], v[186:189], v[44:47]
	v_mfma_f32_16x16x32_bf16 v[36:39], v[166:169], v[186:189], v[36:39]
	v_mfma_f32_16x16x32_bf16 v[28:31], v[158:161], v[194:197], v[28:31]
	v_mfma_f32_16x16x32_bf16 v[20:23], v[166:169], v[194:197], v[20:23]
	v_mfma_f32_16x16x32_bf16 v[12:15], v[158:161], v[202:205], v[12:15]
	v_mfma_f32_16x16x32_bf16 v[4:7], v[166:169], v[202:205], v[4:7]
	v_mfma_f32_16x16x32_bf16 v[60:63], v[162:165], v[182:185], v[60:63]
	v_mfma_f32_16x16x32_bf16 v[52:55], v[170:173], v[182:185], v[52:55]
	v_mfma_f32_16x16x32_bf16 v[44:47], v[162:165], v[190:193], v[44:47]
	v_mfma_f32_16x16x32_bf16 v[36:39], v[170:173], v[190:193], v[36:39]
	v_mfma_f32_16x16x32_bf16 v[28:31], v[162:165], v[198:201], v[28:31]
	v_mfma_f32_16x16x32_bf16 v[20:23], v[170:173], v[198:201], v[20:23]
	v_mfma_f32_16x16x32_bf16 v[12:15], v[162:165], v[206:209], v[12:15]
	v_mfma_f32_16x16x32_bf16 v[4:7], v[170:173], v[206:209], v[4:7]
	s_setprio 0
	s_barrier
	s_add_i32 s51, s51, 2
	s_add_u32 s0, s0, 0x100
	s_addc_u32 s1, s1, 0
	s_add_u32 s49, s49, 0x100
	s_addc_u32 s50, s50, 0
	s_cmp_gt_u32 s51, 13
	s_cbranch_scc0 .LBB0_446
	s_and_b64 vcc, exec, s[18:19]
	s_cbranch_vccz .LBB0_449
	s_barrier
